# residual epilogue (bf16 in/out with next-norm activations): straight-line path, four row groups of residual rows in flight, counted vmcnt, batched cross-lane row-sum reduction
# speedup vs baseline: 1.0079x; 1.0079x over previous
.LBB0_350:
	v_readlane_b32 s64, v254, 33
	v_readlane_b32 s65, v254, 34
	v_readlane_b32 s66, v254, 36
	v_readlane_b32 s67, v254, 37
	s_and_b64 s[64:65], s[64:65], s[66:67]
	s_and_b64 vcc, exec, s[64:65]
	s_cbranch_vccz .Lepr_general
	s_load_dwordx4 s[64:67], s[0:1], 0xb8
	s_lshl_b32 s17, s34, 8
	s_mov_b64 s[52:53], 0x8000
	s_mov_b64 s[14:15], 0x28000
	v_add_u32_e32 v130, s17, v241
	v_ashrrev_i32_e32 v131, 31, v130
	v_lshlrev_b64 v[130:131], 11, v[130:131]
	v_lshl_add_u64 v[130:131], v[220:221], 1, v[130:131]
	s_waitcnt lgkmcnt(0)
	s_add_u32 s54, s66, 0xe800000
	s_addc_u32 s55, s67, 0
	v_lshl_add_u64 v[220:221], v[130:131], 0, s[54:55]
	s_add_u32 s54, s66, 0x6000000
	s_addc_u32 s55, s67, 0
	v_lshl_add_u64 v[218:219], v[130:131], 0, s[54:55]
	v_mov_b32_e32 v216, v220
	v_mov_b32_e32 v217, v221
	global_load_dwordx4 v[154:157], v[220:221], off
	global_load_dwordx4 v[158:161], v[220:221], off offset:256
	v_lshl_add_u64 v[220:221], v[220:221], 0, s[52:53]
	global_load_dwordx4 v[162:165], v[220:221], off
	global_load_dwordx4 v[166:169], v[220:221], off offset:256
	v_lshl_add_u64 v[220:221], v[220:221], 0, s[52:53]
	global_load_dwordx4 v[170:173], v[220:221], off
	global_load_dwordx4 v[174:177], v[220:221], off offset:256
	v_lshl_add_u64 v[220:221], v[220:221], 0, s[52:53]
	global_load_dwordx4 v[130:133], v[220:221], off
	global_load_dwordx4 v[134:137], v[220:221], off offset:256
	v_lshl_add_u64 v[220:221], v[220:221], 0, s[14:15]
	v_pk_mul_f32 v[146:147], v[146:147], v[192:193]
	v_pk_mul_f32 v[148:149], v[148:149], v[192:193]
	v_pk_mul_f32 v[150:151], v[150:151], v[192:193]
	v_pk_mul_f32 v[152:153], v[152:153], v[192:193]
	v_pk_mul_f32 v[138:139], v[138:139], v[192:193]
	v_pk_mul_f32 v[140:141], v[140:141], v[192:193]
	v_pk_mul_f32 v[142:143], v[142:143], v[192:193]
	v_pk_mul_f32 v[144:145], v[144:145], v[192:193]
	s_waitcnt vmcnt(7)
	v_lshlrev_b32_e32 v222, 16, v154
	v_and_b32_e32 v223, 0xffff0000, v154
	v_lshlrev_b32_e32 v224, 16, v156
	v_and_b32_e32 v225, 0xffff0000, v156
	v_lshlrev_b32_e32 v154, 16, v155
	v_and_b32_e32 v155, 0xffff0000, v155
	v_lshlrev_b32_e32 v156, 16, v157
	v_and_b32_e32 v157, 0xffff0000, v157
	v_pk_fma_f32 v[30:31], v[30:31], v[146:147], v[222:223]
	v_pk_fma_f32 v[32:33], v[32:33], v[148:149], v[154:155]
	v_pk_fma_f32 v[26:27], v[26:27], v[150:151], v[224:225]
	v_pk_fma_f32 v[28:29], v[28:29], v[152:153], v[156:157]
	v_cvt_pk_bf16_f32 v222, v30, v31
	v_cvt_pk_bf16_f32 v223, v32, v33
	v_cvt_pk_bf16_f32 v224, v26, v27
	v_cvt_pk_bf16_f32 v225, v28, v29
	global_store_dwordx4 v[216:217], v[222:225], off
	v_pk_mul_f32 v[226:227], v[30:31], v[30:31]
	v_pk_fma_f32 v[226:227], v[32:33], v[32:33], v[226:227]
	v_pk_fma_f32 v[226:227], v[26:27], v[26:27], v[226:227]
	v_pk_fma_f32 v[226:227], v[28:29], v[28:29], v[226:227]
	v_pk_mul_f32 v[30:31], v[30:31], v[208:209]
	v_pk_mul_f32 v[32:33], v[32:33], v[210:211]
	v_pk_mul_f32 v[26:27], v[26:27], v[212:213]
	v_pk_mul_f32 v[28:29], v[28:29], v[214:215]
	v_cvt_pk_bf16_f32 v154, v30, v31
	v_cvt_pk_bf16_f32 v155, v32, v33
	v_cvt_pk_bf16_f32 v156, v26, v27
	v_cvt_pk_bf16_f32 v157, v28, v29
	global_store_dwordx4 v[218:219], v[154:157], off
	s_waitcnt vmcnt(8)
	v_lshlrev_b32_e32 v222, 16, v158
	v_and_b32_e32 v223, 0xffff0000, v158
	v_lshlrev_b32_e32 v224, 16, v160
	v_and_b32_e32 v225, 0xffff0000, v160
	v_lshlrev_b32_e32 v158, 16, v159
	v_and_b32_e32 v159, 0xffff0000, v159
	v_lshlrev_b32_e32 v160, 16, v161
	v_and_b32_e32 v161, 0xffff0000, v161
	v_pk_fma_f32 v[22:23], v[22:23], v[138:139], v[222:223]
	v_pk_fma_f32 v[24:25], v[24:25], v[140:141], v[158:159]
	v_pk_fma_f32 v[14:15], v[14:15], v[142:143], v[224:225]
	v_pk_fma_f32 v[16:17], v[16:17], v[144:145], v[160:161]
	v_cvt_pk_bf16_f32 v222, v22, v23
	v_cvt_pk_bf16_f32 v223, v24, v25
	v_cvt_pk_bf16_f32 v224, v14, v15
	v_cvt_pk_bf16_f32 v225, v16, v17
	global_store_dwordx4 v[216:217], v[222:225], off offset:256
	v_pk_fma_f32 v[226:227], v[22:23], v[22:23], v[226:227]
	v_pk_fma_f32 v[226:227], v[24:25], v[24:25], v[226:227]
	v_pk_fma_f32 v[226:227], v[14:15], v[14:15], v[226:227]
	v_pk_fma_f32 v[226:227], v[16:17], v[16:17], v[226:227]
	v_pk_mul_f32 v[22:23], v[22:23], v[200:201]
	v_pk_mul_f32 v[24:25], v[24:25], v[202:203]
	v_pk_mul_f32 v[14:15], v[14:15], v[204:205]
	v_pk_mul_f32 v[16:17], v[16:17], v[206:207]
	v_cvt_pk_bf16_f32 v158, v22, v23
	v_cvt_pk_bf16_f32 v159, v24, v25
	v_cvt_pk_bf16_f32 v160, v14, v15
	v_cvt_pk_bf16_f32 v161, v16, v17
	global_store_dwordx4 v[218:219], v[158:161], off offset:256
	v_add_f32_e32 v228, v226, v227
	v_lshl_add_u64 v[216:217], v[216:217], 0, s[52:53]
	v_lshl_add_u64 v[218:219], v[218:219], 0, s[52:53]
	global_load_dwordx4 v[154:157], v[220:221], off
	global_load_dwordx4 v[158:161], v[220:221], off offset:256
	v_lshl_add_u64 v[220:221], v[220:221], 0, s[52:53]
	s_waitcnt vmcnt(11)
	v_lshlrev_b32_e32 v222, 16, v162
	v_and_b32_e32 v223, 0xffff0000, v162
	v_lshlrev_b32_e32 v224, 16, v164
	v_and_b32_e32 v225, 0xffff0000, v164
	v_lshlrev_b32_e32 v162, 16, v163
	v_and_b32_e32 v163, 0xffff0000, v163
	v_lshlrev_b32_e32 v164, 16, v165
	v_and_b32_e32 v165, 0xffff0000, v165
	v_pk_fma_f32 v[18:19], v[18:19], v[146:147], v[222:223]
	v_pk_fma_f32 v[20:21], v[20:21], v[148:149], v[162:163]
	v_pk_fma_f32 v[10:11], v[10:11], v[150:151], v[224:225]
	v_pk_fma_f32 v[12:13], v[12:13], v[152:153], v[164:165]
	v_cvt_pk_bf16_f32 v222, v18, v19
	v_cvt_pk_bf16_f32 v223, v20, v21
	v_cvt_pk_bf16_f32 v224, v10, v11
	v_cvt_pk_bf16_f32 v225, v12, v13
	global_store_dwordx4 v[216:217], v[222:225], off
	v_pk_mul_f32 v[226:227], v[18:19], v[18:19]
	v_pk_fma_f32 v[226:227], v[20:21], v[20:21], v[226:227]
	v_pk_fma_f32 v[226:227], v[10:11], v[10:11], v[226:227]
	v_pk_fma_f32 v[226:227], v[12:13], v[12:13], v[226:227]
	v_pk_mul_f32 v[18:19], v[18:19], v[208:209]
	v_pk_mul_f32 v[20:21], v[20:21], v[210:211]
	v_pk_mul_f32 v[10:11], v[10:11], v[212:213]
	v_pk_mul_f32 v[12:13], v[12:13], v[214:215]
	v_cvt_pk_bf16_f32 v162, v18, v19
	v_cvt_pk_bf16_f32 v163, v20, v21
	v_cvt_pk_bf16_f32 v164, v10, v11
	v_cvt_pk_bf16_f32 v165, v12, v13
	global_store_dwordx4 v[218:219], v[162:165], off
	s_waitcnt vmcnt(12)
	v_lshlrev_b32_e32 v222, 16, v166
	v_and_b32_e32 v223, 0xffff0000, v166
	v_lshlrev_b32_e32 v224, 16, v168
	v_and_b32_e32 v225, 0xffff0000, v168
	v_lshlrev_b32_e32 v166, 16, v167
	v_and_b32_e32 v167, 0xffff0000, v167
	v_lshlrev_b32_e32 v168, 16, v169
	v_and_b32_e32 v169, 0xffff0000, v169
	v_pk_fma_f32 v[6:7], v[6:7], v[138:139], v[222:223]
	v_pk_fma_f32 v[8:9], v[8:9], v[140:141], v[166:167]
	v_pk_fma_f32 v[2:3], v[2:3], v[142:143], v[224:225]
	v_pk_fma_f32 v[4:5], v[4:5], v[144:145], v[168:169]
	v_cvt_pk_bf16_f32 v222, v6, v7
	v_cvt_pk_bf16_f32 v223, v8, v9
	v_cvt_pk_bf16_f32 v224, v2, v3
	v_cvt_pk_bf16_f32 v225, v4, v5
	global_store_dwordx4 v[216:217], v[222:225], off offset:256
	v_pk_fma_f32 v[226:227], v[6:7], v[6:7], v[226:227]
	v_pk_fma_f32 v[226:227], v[8:9], v[8:9], v[226:227]
	v_pk_fma_f32 v[226:227], v[2:3], v[2:3], v[226:227]
	v_pk_fma_f32 v[226:227], v[4:5], v[4:5], v[226:227]
	v_pk_mul_f32 v[6:7], v[6:7], v[200:201]
	v_pk_mul_f32 v[8:9], v[8:9], v[202:203]
	v_pk_mul_f32 v[2:3], v[2:3], v[204:205]
	v_pk_mul_f32 v[4:5], v[4:5], v[206:207]
	v_cvt_pk_bf16_f32 v166, v6, v7
	v_cvt_pk_bf16_f32 v167, v8, v9
	v_cvt_pk_bf16_f32 v168, v2, v3
	v_cvt_pk_bf16_f32 v169, v4, v5
	global_store_dwordx4 v[218:219], v[166:169], off offset:256
	v_add_f32_e32 v229, v226, v227
	v_lshl_add_u64 v[216:217], v[216:217], 0, s[52:53]
	v_lshl_add_u64 v[218:219], v[218:219], 0, s[52:53]
	global_load_dwordx4 v[162:165], v[220:221], off
	global_load_dwordx4 v[166:169], v[220:221], off offset:256
	v_lshl_add_u64 v[220:221], v[220:221], 0, s[52:53]
	s_waitcnt vmcnt(15)
	v_lshlrev_b32_e32 v222, 16, v170
	v_and_b32_e32 v223, 0xffff0000, v170
	v_lshlrev_b32_e32 v224, 16, v172
	v_and_b32_e32 v225, 0xffff0000, v172
	v_lshlrev_b32_e32 v170, 16, v171
	v_and_b32_e32 v171, 0xffff0000, v171
	v_lshlrev_b32_e32 v172, 16, v173
	v_and_b32_e32 v173, 0xffff0000, v173
	v_pk_fma_f32 v[126:127], v[126:127], v[146:147], v[222:223]
	v_pk_fma_f32 v[128:129], v[128:129], v[148:149], v[170:171]
	v_pk_fma_f32 v[122:123], v[122:123], v[150:151], v[224:225]
	v_pk_fma_f32 v[124:125], v[124:125], v[152:153], v[172:173]
	v_cvt_pk_bf16_f32 v222, v126, v127
	v_cvt_pk_bf16_f32 v223, v128, v129
	v_cvt_pk_bf16_f32 v224, v122, v123
	v_cvt_pk_bf16_f32 v225, v124, v125
	global_store_dwordx4 v[216:217], v[222:225], off
	v_pk_mul_f32 v[226:227], v[126:127], v[126:127]
	v_pk_fma_f32 v[226:227], v[128:129], v[128:129], v[226:227]
	v_pk_fma_f32 v[226:227], v[122:123], v[122:123], v[226:227]
	v_pk_fma_f32 v[226:227], v[124:125], v[124:125], v[226:227]
	v_pk_mul_f32 v[126:127], v[126:127], v[208:209]
	v_pk_mul_f32 v[128:129], v[128:129], v[210:211]
	v_pk_mul_f32 v[122:123], v[122:123], v[212:213]
	v_pk_mul_f32 v[124:125], v[124:125], v[214:215]
	v_cvt_pk_bf16_f32 v170, v126, v127
	v_cvt_pk_bf16_f32 v171, v128, v129
	v_cvt_pk_bf16_f32 v172, v122, v123
	v_cvt_pk_bf16_f32 v173, v124, v125
	global_store_dwordx4 v[218:219], v[170:173], off
	s_waitcnt vmcnt(16)
	v_lshlrev_b32_e32 v222, 16, v174
	v_and_b32_e32 v223, 0xffff0000, v174
	v_lshlrev_b32_e32 v224, 16, v176
	v_and_b32_e32 v225, 0xffff0000, v176
	v_lshlrev_b32_e32 v174, 16, v175
	v_and_b32_e32 v175, 0xffff0000, v175
	v_lshlrev_b32_e32 v176, 16, v177
	v_and_b32_e32 v177, 0xffff0000, v177
	v_pk_fma_f32 v[118:119], v[118:119], v[138:139], v[222:223]
	v_pk_fma_f32 v[120:121], v[120:121], v[140:141], v[174:175]
	v_pk_fma_f32 v[114:115], v[114:115], v[142:143], v[224:225]
	v_pk_fma_f32 v[116:117], v[116:117], v[144:145], v[176:177]
	v_cvt_pk_bf16_f32 v222, v118, v119
	v_cvt_pk_bf16_f32 v223, v120, v121
	v_cvt_pk_bf16_f32 v224, v114, v115
	v_cvt_pk_bf16_f32 v225, v116, v117
	global_store_dwordx4 v[216:217], v[222:225], off offset:256
	v_pk_fma_f32 v[226:227], v[118:119], v[118:119], v[226:227]
	v_pk_fma_f32 v[226:227], v[120:121], v[120:121], v[226:227]
	v_pk_fma_f32 v[226:227], v[114:115], v[114:115], v[226:227]
	v_pk_fma_f32 v[226:227], v[116:117], v[116:117], v[226:227]
	v_pk_mul_f32 v[118:119], v[118:119], v[200:201]
	v_pk_mul_f32 v[120:121], v[120:121], v[202:203]
	v_pk_mul_f32 v[114:115], v[114:115], v[204:205]
	v_pk_mul_f32 v[116:117], v[116:117], v[206:207]
	v_cvt_pk_bf16_f32 v174, v118, v119
	v_cvt_pk_bf16_f32 v175, v120, v121
	v_cvt_pk_bf16_f32 v176, v114, v115
	v_cvt_pk_bf16_f32 v177, v116, v117
	global_store_dwordx4 v[218:219], v[174:177], off offset:256
	v_add_f32_e32 v22, v226, v227
	v_lshl_add_u64 v[216:217], v[216:217], 0, s[52:53]
	v_lshl_add_u64 v[218:219], v[218:219], 0, s[52:53]
	global_load_dwordx4 v[170:173], v[220:221], off
	global_load_dwordx4 v[174:177], v[220:221], off offset:256
	v_lshl_add_u64 v[220:221], v[220:221], 0, s[52:53]
	s_waitcnt vmcnt(19)
	v_lshlrev_b32_e32 v222, 16, v130
	v_and_b32_e32 v223, 0xffff0000, v130
	v_lshlrev_b32_e32 v224, 16, v132
	v_and_b32_e32 v225, 0xffff0000, v132
	v_lshlrev_b32_e32 v130, 16, v131
	v_and_b32_e32 v131, 0xffff0000, v131
	v_lshlrev_b32_e32 v132, 16, v133
	v_and_b32_e32 v133, 0xffff0000, v133
	v_pk_fma_f32 v[110:111], v[110:111], v[146:147], v[222:223]
	v_pk_fma_f32 v[112:113], v[112:113], v[148:149], v[130:131]
	v_pk_fma_f32 v[106:107], v[106:107], v[150:151], v[224:225]
	v_pk_fma_f32 v[108:109], v[108:109], v[152:153], v[132:133]
	v_cvt_pk_bf16_f32 v222, v110, v111
	v_cvt_pk_bf16_f32 v223, v112, v113
	v_cvt_pk_bf16_f32 v224, v106, v107
	v_cvt_pk_bf16_f32 v225, v108, v109
	global_store_dwordx4 v[216:217], v[222:225], off
	v_pk_mul_f32 v[226:227], v[110:111], v[110:111]
	v_pk_fma_f32 v[226:227], v[112:113], v[112:113], v[226:227]
	v_pk_fma_f32 v[226:227], v[106:107], v[106:107], v[226:227]
	v_pk_fma_f32 v[226:227], v[108:109], v[108:109], v[226:227]
	v_pk_mul_f32 v[110:111], v[110:111], v[208:209]
	v_pk_mul_f32 v[112:113], v[112:113], v[210:211]
	v_pk_mul_f32 v[106:107], v[106:107], v[212:213]
	v_pk_mul_f32 v[108:109], v[108:109], v[214:215]
	v_cvt_pk_bf16_f32 v130, v110, v111
	v_cvt_pk_bf16_f32 v131, v112, v113
	v_cvt_pk_bf16_f32 v132, v106, v107
	v_cvt_pk_bf16_f32 v133, v108, v109
	global_store_dwordx4 v[218:219], v[130:133], off
	s_waitcnt vmcnt(20)
	v_lshlrev_b32_e32 v222, 16, v134
	v_and_b32_e32 v223, 0xffff0000, v134
	v_lshlrev_b32_e32 v224, 16, v136
	v_and_b32_e32 v225, 0xffff0000, v136
	v_lshlrev_b32_e32 v134, 16, v135
	v_and_b32_e32 v135, 0xffff0000, v135
	v_lshlrev_b32_e32 v136, 16, v137
	v_and_b32_e32 v137, 0xffff0000, v137
	v_pk_fma_f32 v[102:103], v[102:103], v[138:139], v[222:223]
	v_pk_fma_f32 v[104:105], v[104:105], v[140:141], v[134:135]
	v_pk_fma_f32 v[98:99], v[98:99], v[142:143], v[224:225]
	v_pk_fma_f32 v[100:101], v[100:101], v[144:145], v[136:137]
	v_cvt_pk_bf16_f32 v222, v102, v103
	v_cvt_pk_bf16_f32 v223, v104, v105
	v_cvt_pk_bf16_f32 v224, v98, v99
	v_cvt_pk_bf16_f32 v225, v100, v101
	global_store_dwordx4 v[216:217], v[222:225], off offset:256
	v_pk_fma_f32 v[226:227], v[102:103], v[102:103], v[226:227]
	v_pk_fma_f32 v[226:227], v[104:105], v[104:105], v[226:227]
	v_pk_fma_f32 v[226:227], v[98:99], v[98:99], v[226:227]
	v_pk_fma_f32 v[226:227], v[100:101], v[100:101], v[226:227]
	v_pk_mul_f32 v[102:103], v[102:103], v[200:201]
	v_pk_mul_f32 v[104:105], v[104:105], v[202:203]
	v_pk_mul_f32 v[98:99], v[98:99], v[204:205]
	v_pk_mul_f32 v[100:101], v[100:101], v[206:207]
	v_cvt_pk_bf16_f32 v134, v102, v103
	v_cvt_pk_bf16_f32 v135, v104, v105
	v_cvt_pk_bf16_f32 v136, v98, v99
	v_cvt_pk_bf16_f32 v137, v100, v101
	global_store_dwordx4 v[218:219], v[134:137], off offset:256
	v_add_f32_e32 v23, v226, v227
	v_lshl_add_u64 v[216:217], v[216:217], 0, s[14:15]
	v_lshl_add_u64 v[218:219], v[218:219], 0, s[14:15]
	global_load_dwordx4 v[130:133], v[220:221], off
	global_load_dwordx4 v[134:137], v[220:221], off offset:256
	s_waitcnt vmcnt(19)
	v_lshlrev_b32_e32 v222, 16, v154
	v_and_b32_e32 v223, 0xffff0000, v154
	v_lshlrev_b32_e32 v224, 16, v156
	v_and_b32_e32 v225, 0xffff0000, v156
	v_lshlrev_b32_e32 v154, 16, v155
	v_and_b32_e32 v155, 0xffff0000, v155
	v_lshlrev_b32_e32 v156, 16, v157
	v_and_b32_e32 v157, 0xffff0000, v157
	v_pk_fma_f32 v[94:95], v[94:95], v[146:147], v[222:223]
	v_pk_fma_f32 v[96:97], v[96:97], v[148:149], v[154:155]
	v_pk_fma_f32 v[90:91], v[90:91], v[150:151], v[224:225]
	v_pk_fma_f32 v[92:93], v[92:93], v[152:153], v[156:157]
	v_cvt_pk_bf16_f32 v222, v94, v95
	v_cvt_pk_bf16_f32 v223, v96, v97
	v_cvt_pk_bf16_f32 v224, v90, v91
	v_cvt_pk_bf16_f32 v225, v92, v93
	global_store_dwordx4 v[216:217], v[222:225], off
	v_pk_mul_f32 v[226:227], v[94:95], v[94:95]
	v_pk_fma_f32 v[226:227], v[96:97], v[96:97], v[226:227]
	v_pk_fma_f32 v[226:227], v[90:91], v[90:91], v[226:227]
	v_pk_fma_f32 v[226:227], v[92:93], v[92:93], v[226:227]
	v_pk_mul_f32 v[94:95], v[94:95], v[208:209]
	v_pk_mul_f32 v[96:97], v[96:97], v[210:211]
	v_pk_mul_f32 v[90:91], v[90:91], v[212:213]
	v_pk_mul_f32 v[92:93], v[92:93], v[214:215]
	v_cvt_pk_bf16_f32 v154, v94, v95
	v_cvt_pk_bf16_f32 v155, v96, v97
	v_cvt_pk_bf16_f32 v156, v90, v91
	v_cvt_pk_bf16_f32 v157, v92, v93
	global_store_dwordx4 v[218:219], v[154:157], off
	s_waitcnt vmcnt(20)
	v_lshlrev_b32_e32 v222, 16, v158
	v_and_b32_e32 v223, 0xffff0000, v158
	v_lshlrev_b32_e32 v224, 16, v160
	v_and_b32_e32 v225, 0xffff0000, v160
	v_lshlrev_b32_e32 v158, 16, v159
	v_and_b32_e32 v159, 0xffff0000, v159
	v_lshlrev_b32_e32 v160, 16, v161
	v_and_b32_e32 v161, 0xffff0000, v161
	v_pk_fma_f32 v[86:87], v[86:87], v[138:139], v[222:223]
	v_pk_fma_f32 v[88:89], v[88:89], v[140:141], v[158:159]
	v_pk_fma_f32 v[82:83], v[82:83], v[142:143], v[224:225]
	v_pk_fma_f32 v[84:85], v[84:85], v[144:145], v[160:161]
	v_cvt_pk_bf16_f32 v222, v86, v87
	v_cvt_pk_bf16_f32 v223, v88, v89
	v_cvt_pk_bf16_f32 v224, v82, v83
	v_cvt_pk_bf16_f32 v225, v84, v85
	global_store_dwordx4 v[216:217], v[222:225], off offset:256
	v_pk_fma_f32 v[226:227], v[86:87], v[86:87], v[226:227]
	v_pk_fma_f32 v[226:227], v[88:89], v[88:89], v[226:227]
	v_pk_fma_f32 v[226:227], v[82:83], v[82:83], v[226:227]
	v_pk_fma_f32 v[226:227], v[84:85], v[84:85], v[226:227]
	v_pk_mul_f32 v[86:87], v[86:87], v[200:201]
	v_pk_mul_f32 v[88:89], v[88:89], v[202:203]
	v_pk_mul_f32 v[82:83], v[82:83], v[204:205]
	v_pk_mul_f32 v[84:85], v[84:85], v[206:207]
	v_cvt_pk_bf16_f32 v158, v86, v87
	v_cvt_pk_bf16_f32 v159, v88, v89
	v_cvt_pk_bf16_f32 v160, v82, v83
	v_cvt_pk_bf16_f32 v161, v84, v85
	global_store_dwordx4 v[218:219], v[158:161], off offset:256
	v_add_f32_e32 v24, v226, v227
	v_lshl_add_u64 v[216:217], v[216:217], 0, s[52:53]
	v_lshl_add_u64 v[218:219], v[218:219], 0, s[52:53]
	s_waitcnt vmcnt(17)
	v_lshlrev_b32_e32 v222, 16, v162
	v_and_b32_e32 v223, 0xffff0000, v162
	v_lshlrev_b32_e32 v224, 16, v164
	v_and_b32_e32 v225, 0xffff0000, v164
	v_lshlrev_b32_e32 v162, 16, v163
	v_and_b32_e32 v163, 0xffff0000, v163
	v_lshlrev_b32_e32 v164, 16, v165
	v_and_b32_e32 v165, 0xffff0000, v165
	v_pk_fma_f32 v[78:79], v[78:79], v[146:147], v[222:223]
	v_pk_fma_f32 v[80:81], v[80:81], v[148:149], v[162:163]
	v_pk_fma_f32 v[74:75], v[74:75], v[150:151], v[224:225]
	v_pk_fma_f32 v[76:77], v[76:77], v[152:153], v[164:165]
	v_cvt_pk_bf16_f32 v222, v78, v79
	v_cvt_pk_bf16_f32 v223, v80, v81
	v_cvt_pk_bf16_f32 v224, v74, v75
	v_cvt_pk_bf16_f32 v225, v76, v77
	global_store_dwordx4 v[216:217], v[222:225], off
	v_pk_mul_f32 v[226:227], v[78:79], v[78:79]
	v_pk_fma_f32 v[226:227], v[80:81], v[80:81], v[226:227]
	v_pk_fma_f32 v[226:227], v[74:75], v[74:75], v[226:227]
	v_pk_fma_f32 v[226:227], v[76:77], v[76:77], v[226:227]
	v_pk_mul_f32 v[78:79], v[78:79], v[208:209]
	v_pk_mul_f32 v[80:81], v[80:81], v[210:211]
	v_pk_mul_f32 v[74:75], v[74:75], v[212:213]
	v_pk_mul_f32 v[76:77], v[76:77], v[214:215]
	v_cvt_pk_bf16_f32 v162, v78, v79
	v_cvt_pk_bf16_f32 v163, v80, v81
	v_cvt_pk_bf16_f32 v164, v74, v75
	v_cvt_pk_bf16_f32 v165, v76, v77
	global_store_dwordx4 v[218:219], v[162:165], off
	s_waitcnt vmcnt(18)
	v_lshlrev_b32_e32 v222, 16, v166
	v_and_b32_e32 v223, 0xffff0000, v166
	v_lshlrev_b32_e32 v224, 16, v168
	v_and_b32_e32 v225, 0xffff0000, v168
	v_lshlrev_b32_e32 v166, 16, v167
	v_and_b32_e32 v167, 0xffff0000, v167
	v_lshlrev_b32_e32 v168, 16, v169
	v_and_b32_e32 v169, 0xffff0000, v169
	v_pk_fma_f32 v[70:71], v[70:71], v[138:139], v[222:223]
	v_pk_fma_f32 v[72:73], v[72:73], v[140:141], v[166:167]
	v_pk_fma_f32 v[66:67], v[66:67], v[142:143], v[224:225]
	v_pk_fma_f32 v[68:69], v[68:69], v[144:145], v[168:169]
	v_cvt_pk_bf16_f32 v222, v70, v71
	v_cvt_pk_bf16_f32 v223, v72, v73
	v_cvt_pk_bf16_f32 v224, v66, v67
	v_cvt_pk_bf16_f32 v225, v68, v69
	global_store_dwordx4 v[216:217], v[222:225], off offset:256
	v_pk_fma_f32 v[226:227], v[70:71], v[70:71], v[226:227]
	v_pk_fma_f32 v[226:227], v[72:73], v[72:73], v[226:227]
	v_pk_fma_f32 v[226:227], v[66:67], v[66:67], v[226:227]
	v_pk_fma_f32 v[226:227], v[68:69], v[68:69], v[226:227]
	v_pk_mul_f32 v[70:71], v[70:71], v[200:201]
	v_pk_mul_f32 v[72:73], v[72:73], v[202:203]
	v_pk_mul_f32 v[66:67], v[66:67], v[204:205]
	v_pk_mul_f32 v[68:69], v[68:69], v[206:207]
	v_cvt_pk_bf16_f32 v166, v70, v71
	v_cvt_pk_bf16_f32 v167, v72, v73
	v_cvt_pk_bf16_f32 v168, v66, v67
	v_cvt_pk_bf16_f32 v169, v68, v69
	global_store_dwordx4 v[218:219], v[166:169], off offset:256
	v_add_f32_e32 v25, v226, v227
	v_lshl_add_u64 v[216:217], v[216:217], 0, s[52:53]
	v_lshl_add_u64 v[218:219], v[218:219], 0, s[52:53]
	s_waitcnt vmcnt(15)
	v_lshlrev_b32_e32 v222, 16, v170
	v_and_b32_e32 v223, 0xffff0000, v170
	v_lshlrev_b32_e32 v224, 16, v172
	v_and_b32_e32 v225, 0xffff0000, v172
	v_lshlrev_b32_e32 v170, 16, v171
	v_and_b32_e32 v171, 0xffff0000, v171
	v_lshlrev_b32_e32 v172, 16, v173
	v_and_b32_e32 v173, 0xffff0000, v173
	v_pk_fma_f32 v[62:63], v[62:63], v[146:147], v[222:223]
	v_pk_fma_f32 v[64:65], v[64:65], v[148:149], v[170:171]
	v_pk_fma_f32 v[58:59], v[58:59], v[150:151], v[224:225]
	v_pk_fma_f32 v[60:61], v[60:61], v[152:153], v[172:173]
	v_cvt_pk_bf16_f32 v222, v62, v63
	v_cvt_pk_bf16_f32 v223, v64, v65
	v_cvt_pk_bf16_f32 v224, v58, v59
	v_cvt_pk_bf16_f32 v225, v60, v61
	global_store_dwordx4 v[216:217], v[222:225], off
	v_pk_mul_f32 v[226:227], v[62:63], v[62:63]
	v_pk_fma_f32 v[226:227], v[64:65], v[64:65], v[226:227]
	v_pk_fma_f32 v[226:227], v[58:59], v[58:59], v[226:227]
	v_pk_fma_f32 v[226:227], v[60:61], v[60:61], v[226:227]
	v_pk_mul_f32 v[62:63], v[62:63], v[208:209]
	v_pk_mul_f32 v[64:65], v[64:65], v[210:211]
	v_pk_mul_f32 v[58:59], v[58:59], v[212:213]
	v_pk_mul_f32 v[60:61], v[60:61], v[214:215]
	v_cvt_pk_bf16_f32 v170, v62, v63
	v_cvt_pk_bf16_f32 v171, v64, v65
	v_cvt_pk_bf16_f32 v172, v58, v59
	v_cvt_pk_bf16_f32 v173, v60, v61
	global_store_dwordx4 v[218:219], v[170:173], off
	s_waitcnt vmcnt(16)
	v_lshlrev_b32_e32 v222, 16, v174
	v_and_b32_e32 v223, 0xffff0000, v174
	v_lshlrev_b32_e32 v224, 16, v176
	v_and_b32_e32 v225, 0xffff0000, v176
	v_lshlrev_b32_e32 v174, 16, v175
	v_and_b32_e32 v175, 0xffff0000, v175
	v_lshlrev_b32_e32 v176, 16, v177
	v_and_b32_e32 v177, 0xffff0000, v177
	v_pk_fma_f32 v[54:55], v[54:55], v[138:139], v[222:223]
	v_pk_fma_f32 v[56:57], v[56:57], v[140:141], v[174:175]
	v_pk_fma_f32 v[50:51], v[50:51], v[142:143], v[224:225]
	v_pk_fma_f32 v[52:53], v[52:53], v[144:145], v[176:177]
	v_cvt_pk_bf16_f32 v222, v54, v55
	v_cvt_pk_bf16_f32 v223, v56, v57
	v_cvt_pk_bf16_f32 v224, v50, v51
	v_cvt_pk_bf16_f32 v225, v52, v53
	global_store_dwordx4 v[216:217], v[222:225], off offset:256
	v_pk_fma_f32 v[226:227], v[54:55], v[54:55], v[226:227]
	v_pk_fma_f32 v[226:227], v[56:57], v[56:57], v[226:227]
	v_pk_fma_f32 v[226:227], v[50:51], v[50:51], v[226:227]
	v_pk_fma_f32 v[226:227], v[52:53], v[52:53], v[226:227]
	v_pk_mul_f32 v[54:55], v[54:55], v[200:201]
	v_pk_mul_f32 v[56:57], v[56:57], v[202:203]
	v_pk_mul_f32 v[50:51], v[50:51], v[204:205]
	v_pk_mul_f32 v[52:53], v[52:53], v[206:207]
	v_cvt_pk_bf16_f32 v174, v54, v55
	v_cvt_pk_bf16_f32 v175, v56, v57
	v_cvt_pk_bf16_f32 v176, v50, v51
	v_cvt_pk_bf16_f32 v177, v52, v53
	global_store_dwordx4 v[218:219], v[174:177], off offset:256
	v_add_f32_e32 v26, v226, v227
	v_lshl_add_u64 v[216:217], v[216:217], 0, s[52:53]
	v_lshl_add_u64 v[218:219], v[218:219], 0, s[52:53]
	s_waitcnt vmcnt(13)
	v_lshlrev_b32_e32 v222, 16, v130
	v_and_b32_e32 v223, 0xffff0000, v130
	v_lshlrev_b32_e32 v224, 16, v132
	v_and_b32_e32 v225, 0xffff0000, v132
	v_lshlrev_b32_e32 v130, 16, v131
	v_and_b32_e32 v131, 0xffff0000, v131
	v_lshlrev_b32_e32 v132, 16, v133
	v_and_b32_e32 v133, 0xffff0000, v133
	v_pk_fma_f32 v[46:47], v[46:47], v[146:147], v[222:223]
	v_pk_fma_f32 v[48:49], v[48:49], v[148:149], v[130:131]
	v_pk_fma_f32 v[42:43], v[42:43], v[150:151], v[224:225]
	v_pk_fma_f32 v[44:45], v[44:45], v[152:153], v[132:133]
	v_cvt_pk_bf16_f32 v222, v46, v47
	v_cvt_pk_bf16_f32 v223, v48, v49
	v_cvt_pk_bf16_f32 v224, v42, v43
	v_cvt_pk_bf16_f32 v225, v44, v45
	global_store_dwordx4 v[216:217], v[222:225], off
	v_pk_mul_f32 v[226:227], v[46:47], v[46:47]
	v_pk_fma_f32 v[226:227], v[48:49], v[48:49], v[226:227]
	v_pk_fma_f32 v[226:227], v[42:43], v[42:43], v[226:227]
	v_pk_fma_f32 v[226:227], v[44:45], v[44:45], v[226:227]
	v_pk_mul_f32 v[46:47], v[46:47], v[208:209]
	v_pk_mul_f32 v[48:49], v[48:49], v[210:211]
	v_pk_mul_f32 v[42:43], v[42:43], v[212:213]
	v_pk_mul_f32 v[44:45], v[44:45], v[214:215]
	v_cvt_pk_bf16_f32 v130, v46, v47
	v_cvt_pk_bf16_f32 v131, v48, v49
	v_cvt_pk_bf16_f32 v132, v42, v43
	v_cvt_pk_bf16_f32 v133, v44, v45
	global_store_dwordx4 v[218:219], v[130:133], off
	s_waitcnt vmcnt(14)
	v_lshlrev_b32_e32 v222, 16, v134
	v_and_b32_e32 v223, 0xffff0000, v134
	v_lshlrev_b32_e32 v224, 16, v136
	v_and_b32_e32 v225, 0xffff0000, v136
	v_lshlrev_b32_e32 v134, 16, v135
	v_and_b32_e32 v135, 0xffff0000, v135
	v_lshlrev_b32_e32 v136, 16, v137
	v_and_b32_e32 v137, 0xffff0000, v137
	v_pk_fma_f32 v[38:39], v[38:39], v[138:139], v[222:223]
	v_pk_fma_f32 v[40:41], v[40:41], v[140:141], v[134:135]
	v_pk_fma_f32 v[34:35], v[34:35], v[142:143], v[224:225]
	v_pk_fma_f32 v[36:37], v[36:37], v[144:145], v[136:137]
	v_cvt_pk_bf16_f32 v222, v38, v39
	v_cvt_pk_bf16_f32 v223, v40, v41
	v_cvt_pk_bf16_f32 v224, v34, v35
	v_cvt_pk_bf16_f32 v225, v36, v37
	global_store_dwordx4 v[216:217], v[222:225], off offset:256
	v_pk_fma_f32 v[226:227], v[38:39], v[38:39], v[226:227]
	v_pk_fma_f32 v[226:227], v[40:41], v[40:41], v[226:227]
	v_pk_fma_f32 v[226:227], v[34:35], v[34:35], v[226:227]
	v_pk_fma_f32 v[226:227], v[36:37], v[36:37], v[226:227]
	v_pk_mul_f32 v[38:39], v[38:39], v[200:201]
	v_pk_mul_f32 v[40:41], v[40:41], v[202:203]
	v_pk_mul_f32 v[34:35], v[34:35], v[204:205]
	v_pk_mul_f32 v[36:37], v[36:37], v[206:207]
	v_cvt_pk_bf16_f32 v134, v38, v39
	v_cvt_pk_bf16_f32 v135, v40, v41
	v_cvt_pk_bf16_f32 v136, v34, v35
	v_cvt_pk_bf16_f32 v137, v36, v37
	global_store_dwordx4 v[218:219], v[134:137], off offset:256
	v_add_f32_e32 v27, v226, v227
	ds_bpermute_b32 v28, v244, v228
	ds_bpermute_b32 v29, v244, v229
	ds_bpermute_b32 v30, v244, v22
	ds_bpermute_b32 v31, v244, v23
	ds_bpermute_b32 v32, v244, v24
	ds_bpermute_b32 v33, v244, v25
	ds_bpermute_b32 v14, v244, v26
	ds_bpermute_b32 v15, v244, v27
	v_readlane_b32 s12, v254, 44
	s_waitcnt lgkmcnt(0)
	v_add_f32_e32 v228, v228, v28
	v_add_f32_e32 v229, v229, v29
	v_add_f32_e32 v22, v22, v30
	v_add_f32_e32 v23, v23, v31
	v_add_f32_e32 v24, v24, v32
	v_add_f32_e32 v25, v25, v33
	v_add_f32_e32 v26, v26, v14
	v_add_f32_e32 v27, v27, v15
	ds_bpermute_b32 v28, v245, v228
	ds_bpermute_b32 v29, v245, v229
	ds_bpermute_b32 v30, v245, v22
	ds_bpermute_b32 v31, v245, v23
	ds_bpermute_b32 v32, v245, v24
	ds_bpermute_b32 v33, v245, v25
	ds_bpermute_b32 v14, v245, v26
	ds_bpermute_b32 v15, v245, v27
	v_lshl_add_u32 v0, v241, 4, s12
	s_waitcnt lgkmcnt(0)
	v_add_f32_e32 v228, v228, v28
	v_add_f32_e32 v229, v229, v29
	v_add_f32_e32 v22, v22, v30
	v_add_f32_e32 v23, v23, v31
	v_add_f32_e32 v24, v24, v32
	v_add_f32_e32 v25, v25, v33
	v_add_f32_e32 v26, v26, v14
	v_add_f32_e32 v27, v27, v15
	s_and_saveexec_b64 s[10:11], s[88:89]
	ds_write_b32 v0, v228
	ds_write_b32 v0, v229 offset:256
	ds_write_b32 v0, v22 offset:512
	ds_write_b32 v0, v23 offset:768
	ds_write_b32 v0, v24 offset:2048
	ds_write_b32 v0, v25 offset:2304
	ds_write_b32 v0, v26 offset:2560
	ds_write_b32 v0, v27 offset:2816
	v_readlane_b32 s72, v253, 57
	v_readlane_b32 s73, v253, 58
	v_readlane_b32 s80, v254, 51
	v_readlane_b32 s81, v254, 52
	v_readlane_b32 s66, v254, 58
	v_readlane_b32 s67, v254, 59
	v_readlane_b32 s54, v253, 59
	v_readlane_b32 s55, v253, 60
	s_branch .LBB0_503
